# P12 wide row pass: final output stores plain instead of non-temporal
# baseline (speedup 1.0000x reference)
; __device__ __forceinline__ f32x4 up4(u32x2 w) { return (f32x4){bf_lo(w.x), bf_hi(w.x), bf_lo(w.y), bf_hi(w.y)}; }
; __device__ __forceinline__ void row_pass1(const Args& a, int row_lo, int row_hi, int gw, int NGW, int lane) {
;     ...
;         for (int r = 0; r < 2; ++r) { const int row = r0 + r; if (row >= row_hi) break;
;             const float rstd = rsqrtf(rs[r] * (1.f / DM) + EPS); f32x4 v[4]; float s = 0.f;
; #pragma unroll
;             for (int j = 0; j < 4; ++j) { v[j] = xv[r][j] + up4(yv[r][j]) * rstd * gp[j]; s += (v[j][0] * v[j][0] + v[j][1] * v[j][1]) + (v[j][2] * v[j][2] + v[j][3] * v[j][3]); }
; template <bool DRYR = false>
; __device__ __forceinline__ void row_pass2(const Args& a, int row_lo, int row_hi, int gw, int NGW, int lane) {
;     ...
;     for (int r0 = row_lo + 2 * gw; r0 < row_hi; r0 += 2 * NGW) {
;         f32x4 xv[2][4]; u32x2 fv[2][4]; float rs[2];
; #pragma unroll
;         for (int r = 0; r < 2; ++r) { const int row = (r0 + r < row_hi) ? r0 + r : r0; rs[r] = rss[row];
;             const f32x4* xo = (const f32x4*)(XO + (size_t)row * DM) + lane; const u32x2* fr = (const u32x2*)(F + (size_t)row * DM) + lane;
; #pragma unroll
;             for (int j = 0; j < 4; ++j) { xv[r][j] = xo[64 * j]; fv[r][j] = fr[64 * j]; } }
; #pragma unroll
;         for (int r = 0; r < 2; ++r) { const int row = r0 + r; if (row >= row_hi) break;
;             const float rstd = rsqrtf(rs[r] * (1.f / DM) + EPS); f32x4* xo = (f32x4*)(XO + (size_t)row * DM) + lane;
; #pragma unroll
;             for (int j = 0; j < 4; ++j) { const f32x4 o = xv[r][j] + up4(fv[r][j]) * rstd * gp[j]; if (!DRYR || o[0] == 123.456f) xo[64 * j] = o; } }
.Lxo_loop:
	global_load_dwordx2 v[80:81], v145, s[16:17]
	global_load_dwordx2 v[82:83], v145, s[18:19]
	global_load_dwordx4 v[48:51], v144, s[24:25] nt
	global_load_dwordx4 v[52:55], v144, s[24:25] offset:1024 nt
	global_load_dwordx4 v[16:19], v148, s[20:21] nt
	global_load_dwordx4 v[20:23], v148, s[20:21] offset:16 nt
	global_load_dwordx4 v[24:27], v148, s[20:21] offset:2048 nt
	global_load_dwordx4 v[28:31], v148, s[20:21] offset:2064 nt
	global_load_dwordx4 v[64:67], v144, s[26:27] nt
	global_load_dwordx4 v[68:71], v144, s[26:27] offset:1024 nt
	global_load_dwordx4 v[56:59], v144, s[24:25] offset:2048 nt
	global_load_dwordx4 v[60:63], v144, s[24:25] offset:3072 nt
	global_load_dwordx4 v[32:35], v149, s[20:21] nt
	global_load_dwordx4 v[36:39], v149, s[20:21] offset:16 nt
	global_load_dwordx4 v[40:43], v149, s[20:21] offset:2048 nt
	global_load_dwordx4 v[44:47], v149, s[20:21] offset:2064 nt
	global_load_dwordx4 v[72:75], v144, s[26:27] offset:2048 nt
	global_load_dwordx4 v[76:79], v144, s[26:27] offset:3072 nt
	s_waitcnt vmcnt(8)
	v_fmamk_f32 v104, v80, 0x3a800000, v116
	v_mul_f32_e32 v105, 0x4b800000, v104
	v_cmp_gt_f32_e32 vcc, s3, v104
	s_nop 1
	v_cndmask_b32_e32 v104, v104, v105, vcc
	v_rsq_f32_e32 v104, v104
	s_nop 0
	v_mul_f32_e32 v105, 0x45800000, v104
	v_cndmask_b32_e32 v104, v104, v105, vcc
	v_fmamk_f32 v106, v82, 0x3a800000, v116
	v_mul_f32_e32 v107, 0x4b800000, v106
	v_cmp_gt_f32_e32 vcc, s3, v106
	s_nop 1
	v_cndmask_b32_e32 v106, v106, v107, vcc
	v_rsq_f32_e32 v106, v106
	s_nop 0
	v_mul_f32_e32 v107, 0x45800000, v106
	v_cndmask_b32_e32 v106, v106, v107, vcc
	v_lshlrev_b32_e32 v120, 16, v48
	v_and_b32_e32 v121, 0xffff0000, v48
	v_lshlrev_b32_e32 v122, 16, v49
	v_and_b32_e32 v123, 0xffff0000, v49
	v_lshlrev_b32_e32 v150, 16, v64
	v_and_b32_e32 v151, 0xffff0000, v64
	v_lshlrev_b32_e32 v152, 16, v65
	v_and_b32_e32 v153, 0xffff0000, v65
	v_pk_mul_f32 v[120:121], v[104:105], v[120:121] op_sel_hi:[0,1]
	v_pk_mul_f32 v[122:123], v[104:105], v[122:123] op_sel_hi:[0,1]
	v_pk_mul_f32 v[150:151], v[106:107], v[150:151] op_sel_hi:[0,1]
	v_pk_mul_f32 v[152:153], v[106:107], v[152:153] op_sel_hi:[0,1]
	v_pk_fma_f32 v[16:17], v[84:85], v[120:121], v[16:17]
	v_pk_fma_f32 v[18:19], v[86:87], v[122:123], v[18:19]
	v_pk_fma_f32 v[16:17], v[0:1], v[150:151], v[16:17]
	v_pk_fma_f32 v[18:19], v[2:3], v[152:153], v[18:19]
	v_lshlrev_b32_e32 v124, 16, v50
	v_and_b32_e32 v125, 0xffff0000, v50
	v_lshlrev_b32_e32 v126, 16, v51
	v_and_b32_e32 v127, 0xffff0000, v51
	v_lshlrev_b32_e32 v154, 16, v66
	v_and_b32_e32 v155, 0xffff0000, v66
	v_lshlrev_b32_e32 v156, 16, v67
	v_and_b32_e32 v157, 0xffff0000, v67
	v_pk_mul_f32 v[124:125], v[104:105], v[124:125] op_sel_hi:[0,1]
	v_pk_mul_f32 v[126:127], v[104:105], v[126:127] op_sel_hi:[0,1]
	v_pk_mul_f32 v[154:155], v[106:107], v[154:155] op_sel_hi:[0,1]
	v_pk_mul_f32 v[156:157], v[106:107], v[156:157] op_sel_hi:[0,1]
	v_pk_fma_f32 v[20:21], v[88:89], v[124:125], v[20:21]
	v_pk_fma_f32 v[22:23], v[90:91], v[126:127], v[22:23]
	v_pk_fma_f32 v[20:21], v[4:5], v[154:155], v[20:21]
	v_pk_fma_f32 v[22:23], v[6:7], v[156:157], v[22:23]
	v_lshlrev_b32_e32 v128, 16, v52
	v_and_b32_e32 v129, 0xffff0000, v52
	v_lshlrev_b32_e32 v130, 16, v53
	v_and_b32_e32 v131, 0xffff0000, v53
	v_lshlrev_b32_e32 v158, 16, v68
	v_and_b32_e32 v159, 0xffff0000, v68
	v_lshlrev_b32_e32 v160, 16, v69
	v_and_b32_e32 v161, 0xffff0000, v69
	v_pk_mul_f32 v[128:129], v[104:105], v[128:129] op_sel_hi:[0,1]
	v_pk_mul_f32 v[130:131], v[104:105], v[130:131] op_sel_hi:[0,1]
	v_pk_mul_f32 v[158:159], v[106:107], v[158:159] op_sel_hi:[0,1]
	v_pk_mul_f32 v[160:161], v[106:107], v[160:161] op_sel_hi:[0,1]
	v_pk_fma_f32 v[24:25], v[92:93], v[128:129], v[24:25]
	v_pk_fma_f32 v[26:27], v[94:95], v[130:131], v[26:27]
	v_pk_fma_f32 v[24:25], v[8:9], v[158:159], v[24:25]
	v_pk_fma_f32 v[26:27], v[10:11], v[160:161], v[26:27]
	v_lshlrev_b32_e32 v132, 16, v54
	v_and_b32_e32 v133, 0xffff0000, v54
	v_lshlrev_b32_e32 v134, 16, v55
	v_and_b32_e32 v135, 0xffff0000, v55
	v_lshlrev_b32_e32 v162, 16, v70
	v_and_b32_e32 v163, 0xffff0000, v70
	v_lshlrev_b32_e32 v164, 16, v71
	v_and_b32_e32 v165, 0xffff0000, v71
	v_pk_mul_f32 v[132:133], v[104:105], v[132:133] op_sel_hi:[0,1]
	v_pk_mul_f32 v[134:135], v[104:105], v[134:135] op_sel_hi:[0,1]
	v_pk_mul_f32 v[162:163], v[106:107], v[162:163] op_sel_hi:[0,1]
	v_pk_mul_f32 v[164:165], v[106:107], v[164:165] op_sel_hi:[0,1]
	v_pk_fma_f32 v[28:29], v[96:97], v[132:133], v[28:29]
	v_pk_fma_f32 v[30:31], v[98:99], v[134:135], v[30:31]
	v_pk_fma_f32 v[28:29], v[12:13], v[162:163], v[28:29]
	v_pk_fma_f32 v[30:31], v[14:15], v[164:165], v[30:31]
	global_store_dwordx4 v148, v[16:19], s[22:23]
	global_store_dwordx4 v148, v[20:23], s[22:23] offset:16
	global_store_dwordx4 v148, v[24:27], s[22:23] offset:2048
	global_store_dwordx4 v148, v[28:31], s[22:23] offset:2064
	s_waitcnt vmcnt(4)
; __device__ __forceinline__ f32x4 up4(u32x2 w) { return (f32x4){bf_lo(w.x), bf_hi(w.x), bf_lo(w.y), bf_hi(w.y)}; }
; __device__ __forceinline__ void row_pass1(const Args& a, int row_lo, int row_hi, int gw, int NGW, int lane) {
;     ...
;         for (int r = 0; r < 2; ++r) { const int row = r0 + r; if (row >= row_hi) break;
;             const float rstd = rsqrtf(rs[r] * (1.f / DM) + EPS); f32x4 v[4]; float s = 0.f;
; #pragma unroll
;             for (int j = 0; j < 4; ++j) { v[j] = xv[r][j] + up4(yv[r][j]) * rstd * gp[j]; s += (v[j][0] * v[j][0] + v[j][1] * v[j][1]) + (v[j][2] * v[j][2] + v[j][3] * v[j][3]); }
; template <bool DRYR = false>
; __device__ __forceinline__ void row_pass2(const Args& a, int row_lo, int row_hi, int gw, int NGW, int lane) {
;     ...
;     for (int r0 = row_lo + 2 * gw; r0 < row_hi; r0 += 2 * NGW) {
;         f32x4 xv[2][4]; u32x2 fv[2][4]; float rs[2];
; #pragma unroll
;         for (int r = 0; r < 2; ++r) { const int row = (r0 + r < row_hi) ? r0 + r : r0; rs[r] = rss[row];
;             const f32x4* xo = (const f32x4*)(XO + (size_t)row * DM) + lane; const u32x2* fr = (const u32x2*)(F + (size_t)row * DM) + lane;
; #pragma unroll
;             for (int j = 0; j < 4; ++j) { xv[r][j] = xo[64 * j]; fv[r][j] = fr[64 * j]; } }
; #pragma unroll
;         for (int r = 0; r < 2; ++r) { const int row = r0 + r; if (row >= row_hi) break;
;             const float rstd = rsqrtf(rs[r] * (1.f / DM) + EPS); f32x4* xo = (f32x4*)(XO + (size_t)row * DM) + lane;
; #pragma unroll
;             for (int j = 0; j < 4; ++j) { const f32x4 o = xv[r][j] + up4(fv[r][j]) * rstd * gp[j]; if (!DRYR || o[0] == 123.456f) xo[64 * j] = o; } }
	v_fmamk_f32 v104, v81, 0x3a800000, v116
	v_mul_f32_e32 v105, 0x4b800000, v104
	v_cmp_gt_f32_e32 vcc, s3, v104
	s_nop 1
	v_cndmask_b32_e32 v104, v104, v105, vcc
	v_rsq_f32_e32 v104, v104
	s_nop 0
	v_mul_f32_e32 v105, 0x45800000, v104
	v_cndmask_b32_e32 v104, v104, v105, vcc
	v_fmamk_f32 v106, v83, 0x3a800000, v116
	v_mul_f32_e32 v107, 0x4b800000, v106
	v_cmp_gt_f32_e32 vcc, s3, v106
	s_nop 1
	v_cndmask_b32_e32 v106, v106, v107, vcc
	v_rsq_f32_e32 v106, v106
	s_nop 0
	v_mul_f32_e32 v107, 0x45800000, v106
	v_cndmask_b32_e32 v106, v106, v107, vcc
	v_lshlrev_b32_e32 v120, 16, v56
	v_and_b32_e32 v121, 0xffff0000, v56
	v_lshlrev_b32_e32 v122, 16, v57
	v_and_b32_e32 v123, 0xffff0000, v57
	v_lshlrev_b32_e32 v150, 16, v72
	v_and_b32_e32 v151, 0xffff0000, v72
	v_lshlrev_b32_e32 v152, 16, v73
	v_and_b32_e32 v153, 0xffff0000, v73
	v_pk_mul_f32 v[120:121], v[104:105], v[120:121] op_sel_hi:[0,1]
	v_pk_mul_f32 v[122:123], v[104:105], v[122:123] op_sel_hi:[0,1]
	v_pk_mul_f32 v[150:151], v[106:107], v[150:151] op_sel_hi:[0,1]
	v_pk_mul_f32 v[152:153], v[106:107], v[152:153] op_sel_hi:[0,1]
	v_pk_fma_f32 v[32:33], v[84:85], v[120:121], v[32:33]
	v_pk_fma_f32 v[34:35], v[86:87], v[122:123], v[34:35]
	v_pk_fma_f32 v[32:33], v[0:1], v[150:151], v[32:33]
	v_pk_fma_f32 v[34:35], v[2:3], v[152:153], v[34:35]
	v_lshlrev_b32_e32 v124, 16, v58
	v_and_b32_e32 v125, 0xffff0000, v58
	v_lshlrev_b32_e32 v126, 16, v59
	v_and_b32_e32 v127, 0xffff0000, v59
	v_lshlrev_b32_e32 v154, 16, v74
	v_and_b32_e32 v155, 0xffff0000, v74
	v_lshlrev_b32_e32 v156, 16, v75
	v_and_b32_e32 v157, 0xffff0000, v75
	v_pk_mul_f32 v[124:125], v[104:105], v[124:125] op_sel_hi:[0,1]
	v_pk_mul_f32 v[126:127], v[104:105], v[126:127] op_sel_hi:[0,1]
	v_pk_mul_f32 v[154:155], v[106:107], v[154:155] op_sel_hi:[0,1]
	v_pk_mul_f32 v[156:157], v[106:107], v[156:157] op_sel_hi:[0,1]
	v_pk_fma_f32 v[36:37], v[88:89], v[124:125], v[36:37]
	v_pk_fma_f32 v[38:39], v[90:91], v[126:127], v[38:39]
	v_pk_fma_f32 v[36:37], v[4:5], v[154:155], v[36:37]
	v_pk_fma_f32 v[38:39], v[6:7], v[156:157], v[38:39]
	v_lshlrev_b32_e32 v128, 16, v60
	v_and_b32_e32 v129, 0xffff0000, v60
	v_lshlrev_b32_e32 v130, 16, v61
	v_and_b32_e32 v131, 0xffff0000, v61
	v_lshlrev_b32_e32 v158, 16, v76
	v_and_b32_e32 v159, 0xffff0000, v76
	v_lshlrev_b32_e32 v160, 16, v77
	v_and_b32_e32 v161, 0xffff0000, v77
	v_pk_mul_f32 v[128:129], v[104:105], v[128:129] op_sel_hi:[0,1]
	v_pk_mul_f32 v[130:131], v[104:105], v[130:131] op_sel_hi:[0,1]
	v_pk_mul_f32 v[158:159], v[106:107], v[158:159] op_sel_hi:[0,1]
	v_pk_mul_f32 v[160:161], v[106:107], v[160:161] op_sel_hi:[0,1]
	v_pk_fma_f32 v[40:41], v[92:93], v[128:129], v[40:41]
	v_pk_fma_f32 v[42:43], v[94:95], v[130:131], v[42:43]
	v_pk_fma_f32 v[40:41], v[8:9], v[158:159], v[40:41]
	v_pk_fma_f32 v[42:43], v[10:11], v[160:161], v[42:43]
	v_lshlrev_b32_e32 v132, 16, v62
	v_and_b32_e32 v133, 0xffff0000, v62
	v_lshlrev_b32_e32 v134, 16, v63
	v_and_b32_e32 v135, 0xffff0000, v63
	v_lshlrev_b32_e32 v162, 16, v78
	v_and_b32_e32 v163, 0xffff0000, v78
	v_lshlrev_b32_e32 v164, 16, v79
	v_and_b32_e32 v165, 0xffff0000, v79
	v_pk_mul_f32 v[132:133], v[104:105], v[132:133] op_sel_hi:[0,1]
	v_pk_mul_f32 v[134:135], v[104:105], v[134:135] op_sel_hi:[0,1]
	v_pk_mul_f32 v[162:163], v[106:107], v[162:163] op_sel_hi:[0,1]
	v_pk_mul_f32 v[164:165], v[106:107], v[164:165] op_sel_hi:[0,1]
	v_pk_fma_f32 v[44:45], v[96:97], v[132:133], v[44:45]
	v_pk_fma_f32 v[46:47], v[98:99], v[134:135], v[46:47]
	v_pk_fma_f32 v[44:45], v[12:13], v[162:163], v[44:45]
	v_pk_fma_f32 v[46:47], v[14:15], v[164:165], v[46:47]
	global_store_dwordx4 v149, v[32:35], s[22:23]
	global_store_dwordx4 v149, v[36:39], s[22:23] offset:16
	global_store_dwordx4 v149, v[40:43], s[22:23] offset:2048
	global_store_dwordx4 v149, v[44:47], s[22:23] offset:2064
	s_add_i32 s0, s0, s4
	s_add_u32 s20, s20, s98
	s_addc_u32 s21, s21, 0
	s_add_u32 s22, s22, s98
	s_addc_u32 s23, s23, 0
	s_add_u32 s24, s24, s99
	s_addc_u32 s25, s25, 0
	s_add_u32 s26, s26, s99
	s_addc_u32 s27, s27, 0
	s_add_u32 s16, s16, s100
	s_addc_u32 s17, s17, 0
	s_add_u32 s18, s18, s100
	s_addc_u32 s19, s19, 0
	s_cmpk_gt_i32 s0, 0x3fff
	s_cbranch_scc0 .Lxo_loop
